# index scoring loop: two accumulator sets so block u+1 MFMAs overlap block u relu/weighted-sum VALU (re-test now that key loads are coalesced)
# speedup vs baseline: 1.0151x; 1.0050x over previous
.LBB0_296:
	s_or_b64 exec, exec, s[6:7]
	v_mfma_f32_32x32x16_bf16 v[2:17], v[18:21], v[2:5], 0
	v_cmp_gt_i32_e64 s[0:1], s94, v197
	v_mfma_f32_32x32x16_bf16 v[2:17], v[22:25], v[166:169], v[2:17]
	v_mfma_f32_32x32x16_bf16 v[2:17], v[26:29], v[170:173], v[2:17]
	v_mfma_f32_32x32x16_bf16 v[2:17], v[30:33], v[162:165], v[2:17]
	v_mfma_f32_32x32x16_bf16 v[216:231], v[18:21], v[154:157], 0
	v_mfma_f32_32x32x16_bf16 v[216:231], v[22:25], v[150:153], v[216:231]
	v_add_u32_e32 v150, 4, v197
	v_cmp_gt_i32_e64 s[18:19], s94, v150
	v_mfma_f32_32x32x16_bf16 v[216:231], v[26:29], v[158:161], v[216:231]
	v_mfma_f32_32x32x16_bf16 v[216:231], v[30:33], v[146:149], v[216:231]
	s_and_saveexec_b64 s[6:7], s[0:1]
	s_cbranch_execz .Lidx_sk0
	s_nop 3
	v_max_f32_e32 v10, 0, v10
	v_max_f32_e32 v11, 0, v11
	v_max_f32_e32 v2, 0, v2
	v_max_f32_e32 v3, 0, v3
	v_pk_mul_f32 v[10:11], v[42:43], v[10:11]
	v_pk_mul_f32 v[2:3], v[34:35], v[2:3]
	v_max_f32_e32 v12, 0, v12
	v_max_f32_e32 v13, 0, v13
	v_max_f32_e32 v4, 0, v4
	v_max_f32_e32 v5, 0, v5
	v_mov_b32_e32 v162, v2
	v_mov_b32_e32 v163, v10
	v_pk_mul_f32 v[12:13], v[44:45], v[12:13]
	v_pk_mul_f32 v[4:5], v[36:37], v[4:5]
	v_pk_add_f32 v[162:163], v[162:163], 0 op_sel_hi:[1,0]
	v_mov_b32_e32 v10, v3
	v_max_f32_e32 v14, 0, v14
	v_max_f32_e32 v15, 0, v15
	v_max_f32_e32 v6, 0, v6
	v_max_f32_e32 v7, 0, v7
	v_pk_add_f32 v[2:3], v[10:11], v[162:163]
	v_mov_b32_e32 v10, v4
	v_mov_b32_e32 v11, v12
	v_pk_mul_f32 v[14:15], v[46:47], v[14:15]
	v_pk_mul_f32 v[6:7], v[38:39], v[6:7]
	v_pk_add_f32 v[2:3], v[10:11], v[2:3]
	v_mov_b32_e32 v12, v5
	v_max_f32_e32 v16, 0, v16
	v_max_f32_e32 v17, 0, v17
	v_max_f32_e32 v8, 0, v8
	v_max_f32_e32 v9, 0, v9
	v_pk_add_f32 v[2:3], v[12:13], v[2:3]
	v_mov_b32_e32 v4, v6
	v_mov_b32_e32 v5, v14
	v_pk_mul_f32 v[16:17], v[48:49], v[16:17]
	v_pk_mul_f32 v[8:9], v[40:41], v[8:9]
	v_pk_add_f32 v[2:3], v[4:5], v[2:3]
	v_mov_b32_e32 v14, v7
	v_pk_add_f32 v[2:3], v[14:15], v[2:3]
	v_mov_b32_e32 v4, v8
	v_mov_b32_e32 v5, v16
	v_pk_add_f32 v[2:3], v[4:5], v[2:3]
	v_mov_b32_e32 v16, v9
	v_pk_add_f32 v[2:3], v[16:17], v[2:3]
	s_nop 0
	v_cmp_neq_f32_e64 s[0:1], 0, v3
	s_nop 1
	v_cndmask_b32_e64 v3, 0, v3, s[0:1]
	v_cmp_neq_f32_e64 s[0:1], 0, v2
	s_nop 1
	v_cndmask_b32_e64 v2, 0, v2, s[0:1]
	ds_write2st64_b32 v0, v2, v3 offset1:64
.Lidx_sk0:
	s_or_b64 exec, exec, s[6:7]
	v_mfma_f32_32x32x16_bf16 v[2:17], v[18:21], v[138:141], 0
	v_mfma_f32_32x32x16_bf16 v[2:17], v[22:25], v[134:137], v[2:17]
	v_add_u32_e32 v134, 8, v197
	v_cmp_gt_i32_e64 s[0:1], s94, v134
	v_mfma_f32_32x32x16_bf16 v[2:17], v[26:29], v[142:145], v[2:17]
	v_mfma_f32_32x32x16_bf16 v[2:17], v[30:33], v[130:133], v[2:17]
	s_and_saveexec_b64 s[6:7], s[18:19]
	s_cbranch_execz .Lidx_sk1
	s_nop 0
	v_max_f32_e32 v224, 0, v224
	v_max_f32_e32 v225, 0, v225
	v_max_f32_e32 v216, 0, v216
	v_max_f32_e32 v217, 0, v217
	v_pk_mul_f32 v[224:225], v[42:43], v[224:225]
	v_pk_mul_f32 v[216:217], v[34:35], v[216:217]
	v_max_f32_e32 v226, 0, v226
	v_max_f32_e32 v227, 0, v227
	v_max_f32_e32 v218, 0, v218
	v_max_f32_e32 v219, 0, v219
	v_mov_b32_e32 v146, v216
	v_mov_b32_e32 v147, v224
	v_pk_mul_f32 v[226:227], v[44:45], v[226:227]
	v_pk_mul_f32 v[218:219], v[36:37], v[218:219]
	v_pk_add_f32 v[146:147], v[146:147], 0 op_sel_hi:[1,0]
	v_mov_b32_e32 v224, v217
	v_max_f32_e32 v228, 0, v228
	v_max_f32_e32 v229, 0, v229
	v_max_f32_e32 v220, 0, v220
	v_max_f32_e32 v221, 0, v221
	v_pk_add_f32 v[216:217], v[224:225], v[146:147]
	v_mov_b32_e32 v224, v218
	v_mov_b32_e32 v225, v226
	v_pk_mul_f32 v[228:229], v[46:47], v[228:229]
	v_pk_mul_f32 v[220:221], v[38:39], v[220:221]
	v_pk_add_f32 v[216:217], v[224:225], v[216:217]
	v_mov_b32_e32 v226, v219
	v_max_f32_e32 v230, 0, v230
	v_max_f32_e32 v231, 0, v231
	v_max_f32_e32 v222, 0, v222
	v_max_f32_e32 v223, 0, v223
	v_pk_add_f32 v[216:217], v[226:227], v[216:217]
	v_mov_b32_e32 v218, v220
	v_mov_b32_e32 v219, v228
	v_pk_mul_f32 v[230:231], v[48:49], v[230:231]
	v_pk_mul_f32 v[222:223], v[40:41], v[222:223]
	v_pk_add_f32 v[216:217], v[218:219], v[216:217]
	v_mov_b32_e32 v228, v221
	v_pk_add_f32 v[216:217], v[228:229], v[216:217]
	v_mov_b32_e32 v218, v222
	v_mov_b32_e32 v219, v230
	v_pk_add_f32 v[216:217], v[218:219], v[216:217]
	v_mov_b32_e32 v230, v223
	v_pk_add_f32 v[216:217], v[230:231], v[216:217]
	s_nop 0
	v_cmp_neq_f32_e64 s[18:19], 0, v217
	s_nop 1
	v_cndmask_b32_e64 v217, 0, v217, s[18:19]
	v_cmp_neq_f32_e64 s[18:19], 0, v216
	s_nop 1
	v_cndmask_b32_e64 v216, 0, v216, s[18:19]
	ds_write2st64_b32 v0, v216, v217 offset0:2 offset1:66
.Lidx_sk1:
	s_or_b64 exec, exec, s[6:7]
	v_mfma_f32_32x32x16_bf16 v[216:231], v[18:21], v[122:125], 0
	v_mfma_f32_32x32x16_bf16 v[216:231], v[22:25], v[118:121], v[216:231]
	v_add_u32_e32 v118, 12, v197
	v_cmp_gt_i32_e64 s[18:19], s94, v118
	v_mfma_f32_32x32x16_bf16 v[216:231], v[26:29], v[126:129], v[216:231]
	v_mfma_f32_32x32x16_bf16 v[216:231], v[30:33], v[114:117], v[216:231]
	s_and_saveexec_b64 s[6:7], s[0:1]
	s_cbranch_execz .Lidx_sk2
	s_nop 0
	v_max_f32_e32 v10, 0, v10
	v_max_f32_e32 v11, 0, v11
	v_max_f32_e32 v2, 0, v2
	v_max_f32_e32 v3, 0, v3
	v_pk_mul_f32 v[10:11], v[42:43], v[10:11]
	v_pk_mul_f32 v[2:3], v[34:35], v[2:3]
	v_max_f32_e32 v12, 0, v12
	v_max_f32_e32 v13, 0, v13
	v_max_f32_e32 v4, 0, v4
	v_max_f32_e32 v5, 0, v5
	v_mov_b32_e32 v130, v2
	v_mov_b32_e32 v131, v10
	v_pk_mul_f32 v[12:13], v[44:45], v[12:13]
	v_pk_mul_f32 v[4:5], v[36:37], v[4:5]
	v_pk_add_f32 v[130:131], v[130:131], 0 op_sel_hi:[1,0]
	v_mov_b32_e32 v10, v3
	v_max_f32_e32 v14, 0, v14
	v_max_f32_e32 v15, 0, v15
	v_max_f32_e32 v6, 0, v6
	v_max_f32_e32 v7, 0, v7
	v_pk_add_f32 v[2:3], v[10:11], v[130:131]
	v_mov_b32_e32 v10, v4
	v_mov_b32_e32 v11, v12
	v_pk_mul_f32 v[14:15], v[46:47], v[14:15]
	v_pk_mul_f32 v[6:7], v[38:39], v[6:7]
	v_pk_add_f32 v[2:3], v[10:11], v[2:3]
	v_mov_b32_e32 v12, v5
	v_max_f32_e32 v16, 0, v16
	v_max_f32_e32 v17, 0, v17
	v_max_f32_e32 v8, 0, v8
	v_max_f32_e32 v9, 0, v9
	v_pk_add_f32 v[2:3], v[12:13], v[2:3]
	v_mov_b32_e32 v4, v6
	v_mov_b32_e32 v5, v14
	v_pk_mul_f32 v[16:17], v[48:49], v[16:17]
	v_pk_mul_f32 v[8:9], v[40:41], v[8:9]
	v_pk_add_f32 v[2:3], v[4:5], v[2:3]
	v_mov_b32_e32 v14, v7
	v_pk_add_f32 v[2:3], v[14:15], v[2:3]
	v_mov_b32_e32 v4, v8
	v_mov_b32_e32 v5, v16
	v_pk_add_f32 v[2:3], v[4:5], v[2:3]
	v_mov_b32_e32 v16, v9
	v_pk_add_f32 v[2:3], v[16:17], v[2:3]
	s_nop 0
	v_cmp_neq_f32_e64 s[0:1], 0, v3
	s_nop 1
	v_cndmask_b32_e64 v3, 0, v3, s[0:1]
	v_cmp_neq_f32_e64 s[0:1], 0, v2
	s_nop 1
	v_cndmask_b32_e64 v2, 0, v2, s[0:1]
	ds_write2st64_b32 v0, v2, v3 offset0:4 offset1:68
.Lidx_sk2:
	s_or_b64 exec, exec, s[6:7]
	s_and_saveexec_b64 s[6:7], s[18:19]
	s_cbranch_execz .Lidx_sk3
	s_nop 0
	v_max_f32_e32 v224, 0, v224
	v_max_f32_e32 v225, 0, v225
	v_max_f32_e32 v216, 0, v216
	v_max_f32_e32 v217, 0, v217
	v_pk_mul_f32 v[224:225], v[42:43], v[224:225]
	v_pk_mul_f32 v[216:217], v[34:35], v[216:217]
	v_max_f32_e32 v226, 0, v226
	v_max_f32_e32 v227, 0, v227
	v_max_f32_e32 v218, 0, v218
	v_max_f32_e32 v219, 0, v219
	v_mov_b32_e32 v114, v216
	v_mov_b32_e32 v115, v224
	v_pk_mul_f32 v[226:227], v[44:45], v[226:227]
	v_pk_mul_f32 v[218:219], v[36:37], v[218:219]
	v_pk_add_f32 v[114:115], v[114:115], 0 op_sel_hi:[1,0]
	v_mov_b32_e32 v224, v217
	v_max_f32_e32 v228, 0, v228
	v_max_f32_e32 v229, 0, v229
	v_max_f32_e32 v220, 0, v220
	v_max_f32_e32 v221, 0, v221
	v_pk_add_f32 v[216:217], v[224:225], v[114:115]
	v_mov_b32_e32 v224, v218
	v_mov_b32_e32 v225, v226
	v_pk_mul_f32 v[228:229], v[46:47], v[228:229]
	v_pk_mul_f32 v[220:221], v[38:39], v[220:221]
	v_pk_add_f32 v[216:217], v[224:225], v[216:217]
	v_mov_b32_e32 v226, v219
	v_max_f32_e32 v230, 0, v230
	v_max_f32_e32 v231, 0, v231
	v_max_f32_e32 v222, 0, v222
	v_max_f32_e32 v223, 0, v223
	v_pk_add_f32 v[216:217], v[226:227], v[216:217]
	v_mov_b32_e32 v218, v220
	v_mov_b32_e32 v219, v228
	v_pk_mul_f32 v[230:231], v[48:49], v[230:231]
	v_pk_mul_f32 v[222:223], v[40:41], v[222:223]
	v_pk_add_f32 v[216:217], v[218:219], v[216:217]
	v_mov_b32_e32 v228, v221
	v_pk_add_f32 v[216:217], v[228:229], v[216:217]
	v_mov_b32_e32 v218, v222
	v_mov_b32_e32 v219, v230
	v_pk_add_f32 v[216:217], v[218:219], v[216:217]
	v_mov_b32_e32 v230, v223
	v_pk_add_f32 v[216:217], v[230:231], v[216:217]
	s_nop 0
	v_cmp_neq_f32_e64 s[18:19], 0, v217
	s_nop 1
	v_cndmask_b32_e64 v217, 0, v217, s[18:19]
	v_cmp_neq_f32_e64 s[18:19], 0, v216
	s_nop 1
	v_cndmask_b32_e64 v216, 0, v216, s[18:19]
	ds_write2st64_b32 v0, v216, v217 offset0:6 offset1:70
.Lidx_sk3:
	s_or_b64 exec, exec, s[6:7]
	s_branch .LBB0_293
